# NSA selected phase A also reads the fragment-major K'/V' copies (coalesced loads)
# speedup vs baseline: 1.0206x; 1.0085x over previous
.LBB0_1143:
	s_or_b64 exec, exec, s[28:29]
	s_lshl_b32 s6, s68, 21
	v_lshl_add_u32 v182, v197, 4, s6
	v_add_u32_e32 v182, 0x1000, v182
	v_mov_b32_e32 v183, 0
	v_lshl_add_u64 v[182:183], s[66:67], 0, v[182:183]
	s_mov_b64 s[6:7], 0x3e78400
	v_lshl_add_u64 v[182:183], v[182:183], 0, s[6:7]
	s_mov_b64 s[6:7], 0x600000
	v_lshl_add_u64 v[184:185], v[182:183], 0, s[6:7]
	s_lshl_b32 s6, s25, 13
	s_mov_b32 s7, 0
	v_lshl_add_u64 v[186:187], v[182:183], 0, s[6:7]
	v_lshl_add_u64 v[188:189], v[184:185], 0, s[6:7]
	s_lshl_b32 s6, s68, 7
	v_readlane_b32 s7, v249, 38
	s_add_u32 s38, s7, s6
	v_readlane_b32 s6, v249, 40
	v_or3_b32 v0, s27, v219, v78
	s_addc_u32 s39, s6, 0
	v_mul_u32_u24_e32 v0, 0x4600, v0
	v_lshl_add_u64 v[2:3], s[38:39], 0, v[0:1]
	v_lshlrev_b32_e32 v0, 1, v170
	v_lshl_add_u64 v[2:3], v[2:3], 0, v[0:1]
	s_mov_b32 s6, 0x11000
	v_add_co_u32_e32 v4, vcc, s6, v2
	s_waitcnt lgkmcnt(0)
	s_barrier
	global_load_dwordx4 v[34:37], v[186:187], off offset:-4096
	v_addc_co_u32_e32 v5, vcc, 0, v3, vcc
	s_mov_b32 s6, 0x8c000
	v_add_co_u32_e32 v6, vcc, s6, v2
	global_load_dwordx4 v[38:41], v[186:187], off offset:-2048
	s_nop 0
	v_addc_co_u32_e32 v7, vcc, 0, v3, vcc
	global_load_dwordx4 v[42:45], v[186:187], off
	s_mov_b32 s6, 0x9d000
	v_add_co_u32_e32 v8, vcc, s6, v2
	s_lshl_b64 s[10:11], s[68:69], 21
	s_nop 0
	v_addc_co_u32_e32 v9, vcc, 0, v3, vcc
	global_load_dwordx4 v[46:49], v[186:187], off offset:2048
	global_load_dwordx4 v[62:65], v[186:187], off offset:-3072
	global_load_dwordx4 v[58:61], v[186:187], off offset:-1024
	global_load_dwordx4 v[54:57], v[186:187], off offset:1024
	global_load_dwordx4 v[50:53], v[186:187], off offset:3072
	ds_read_b128 v[6:9], v81
	ds_read_b128 v[86:89], v82
	v_readlane_b32 s6, v249, 4
	s_add_u32 s10, s6, s10
	v_readlane_b32 s6, v249, 34
	v_lshlrev_b32_e32 v2, 15, v75
	v_mov_b32_e32 v3, v1
	s_addc_u32 s11, s6, s11
	v_lshl_add_u64 v[66:67], s[10:11], 0, v[2:3]
	s_mov_b64 s[10:11], 0x80000
	v_lshl_add_u64 v[68:69], v[66:67], 0, s[10:11]
	s_mov_b64 s[10:11], 0x100000
	s_mov_b32 s7, s69
	s_lshl_b32 s6, s27, 1
	v_lshl_add_u64 v[70:71], v[66:67], 0, s[10:11]
	s_mov_b64 s[10:11], 0x180000
	v_lshl_add_u64 v[2:3], v[66:67], 0, s[6:7]
	v_lshl_add_u64 v[72:73], v[66:67], 0, s[10:11]
	v_lshl_add_u64 v[22:23], v[68:69], 0, s[6:7]
	v_lshl_add_u64 v[2:3], v[2:3], 0, v[0:1]
	v_lshl_add_u64 v[24:25], v[70:71], 0, s[6:7]
	v_lshl_add_u64 v[26:27], v[72:73], 0, s[6:7]
	global_load_dwordx4 v[18:21], v[188:189], off offset:-4096
	s_nop 0
	global_load_dwordx4 v[2:5], v[188:189], off offset:-3072
	v_lshl_add_u64 v[30:31], v[24:25], 0, v[0:1]
	v_lshl_add_u64 v[106:107], v[26:27], 0, v[0:1]
	v_or_b32_e32 v78, s27, v170
	v_sub_u32_e32 v114, v77, v78
	v_cmp_lt_i32_e32 vcc, -1, v114
	v_cmp_gt_u32_e64 s[28:29], 16, v74
	v_lshl_add_u32 v224, v84, 2, 0
	s_waitcnt vmcnt(6) lgkmcnt(1)
	v_mfma_f32_16x16x32_bf16 v[94:97], v[46:49], v[6:9], 0
	v_mfma_f32_16x16x32_bf16 v[10:13], v[34:37], v[6:9], 0
	v_mfma_f32_16x16x32_bf16 v[14:17], v[38:41], v[6:9], 0
	v_mfma_f32_16x16x32_bf16 v[90:93], v[42:45], v[6:9], 0
	v_lshl_add_u64 v[6:7], v[22:23], 0, v[0:1]
	s_waitcnt vmcnt(5) lgkmcnt(0)
	v_mfma_f32_16x16x32_bf16 v[98:101], v[62:65], v[86:89], v[10:13]
	global_load_dwordx4 v[22:25], v[188:189], off offset:-2048
	s_nop 0
	global_load_dwordx4 v[6:9], v[188:189], off offset:-1024
	s_nop 0
	global_load_dwordx4 v[26:29], v[188:189], off
	global_load_dwordx4 v[10:13], v[188:189], off offset:1024
	s_nop 1
	v_cndmask_b32_e32 v77, v201, v98, vcc
	s_waitcnt vmcnt(8)
	v_mfma_f32_16x16x32_bf16 v[102:105], v[58:61], v[86:89], v[14:17]
	global_load_dwordx4 v[30:33], v[188:189], off offset:2048
	s_nop 1
	global_load_dwordx4 v[14:17], v[188:189], off offset:3072
	v_cmp_lt_i32_e32 vcc, 0, v114
	s_waitcnt vmcnt(9)
	v_mfma_f32_16x16x32_bf16 v[106:109], v[54:57], v[86:89], v[90:93]
	v_cndmask_b32_e32 v85, v201, v99, vcc
	v_cmp_lt_i32_e32 vcc, 1, v114
	s_waitcnt vmcnt(8)
	v_mfma_f32_16x16x32_bf16 v[110:113], v[50:53], v[86:89], v[94:97]
	v_cndmask_b32_e32 v86, v201, v100, vcc
	v_cmp_lt_i32_e32 vcc, 2, v114
	s_nop 1
	v_cndmask_b32_e32 v88, v201, v101, vcc
	v_cmp_lt_i32_e32 vcc, 3, v114
	v_max_f32_e32 v100, v88, v88
	v_max_f32_e32 v101, v86, v86
	v_cndmask_b32_e32 v87, v201, v102, vcc
	v_cmp_lt_i32_e32 vcc, 4, v114
	v_max_f32_e32 v100, v101, v100
	v_max3_f32 v100, v77, v85, v100
	v_cndmask_b32_e32 v89, v201, v103, vcc
	v_cmp_lt_i32_e32 vcc, 5, v114
	s_nop 1
	v_cndmask_b32_e32 v90, v201, v104, vcc
	v_cmp_lt_i32_e32 vcc, 6, v114
	s_nop 1
	v_cndmask_b32_e32 v92, v201, v105, vcc
	v_cmp_lt_i32_e32 vcc, 31, v114
	v_max3_f32 v101, v89, v90, v92
	v_max3_f32 v100, v100, v87, v101
	v_cndmask_b32_e32 v91, v201, v106, vcc
	v_cmp_lt_i32_e32 vcc, 32, v114
	s_nop 1
	v_cndmask_b32_e32 v94, v201, v107, vcc
	v_cmp_lt_i32_e32 vcc, 33, v114
	s_nop 1
	v_cndmask_b32_e32 v96, v201, v108, vcc
	v_cmp_lt_i32_e32 vcc, 34, v114
	s_nop 1
	v_cndmask_b32_e32 v97, v201, v109, vcc
	v_cmp_lt_i32_e32 vcc, 35, v114
	v_max3_f32 v101, v94, v96, v97
	v_max3_f32 v100, v100, v91, v101
	v_cndmask_b32_e32 v93, v201, v110, vcc
	v_cmp_lt_i32_e32 vcc, 36, v114
	s_nop 1
	v_cndmask_b32_e32 v95, v201, v111, vcc
	v_cmp_lt_i32_e32 vcc, 37, v114
	s_nop 1
	v_cndmask_b32_e32 v98, v201, v112, vcc
	v_cmp_lt_i32_e32 vcc, 38, v114
	s_nop 1
	v_cndmask_b32_e32 v99, v201, v113, vcc
	v_max3_f32 v101, v95, v98, v99
	v_max3_f32 v100, v100, v93, v101
	v_mov_b32_e32 v101, v100
	s_nop 1
	v_permlane16_swap_b32_e32 v100, v101
	v_max_f32_e32 v101, v101, v101
	v_max_f32_e32 v100, v100, v100
	v_max_f32_e32 v100, v100, v101
	v_mov_b32_e32 v101, v100
	s_nop 1
	v_permlane32_swap_b32_e32 v100, v101
	v_max_f32_e32 v101, v101, v101
	v_max_f32_e32 v100, v100, v100
	v_max_f32_e32 v100, v100, v101
	s_and_saveexec_b64 s[6:7], s[28:29]
	v_add_u32_e32 v101, 0x1d400, v224
	ds_write_b32 v101, v100
	s_or_b64 exec, exec, s[6:7]
	v_add_f32_e32 v100, 0xc1200000, v100
	v_sub_f32_e32 v88, v88, v100
	v_sub_f32_e32 v86, v86, v100
	v_sub_f32_e32 v85, v85, v100
	v_sub_f32_e32 v77, v77, v100
	v_sub_f32_e32 v101, v92, v100
	v_sub_f32_e32 v92, v87, v100
	v_exp_f32_e32 v77, v77
	v_exp_f32_e32 v85, v85
	v_exp_f32_e32 v86, v86
	v_exp_f32_e32 v87, v88
	v_sub_f32_e32 v90, v90, v100
	v_sub_f32_e32 v89, v89, v100
	v_sub_f32_e32 v102, v91, v100
	v_sub_f32_e32 v103, v95, v100
	v_exp_f32_e32 v88, v92
	v_exp_f32_e32 v91, v89
	v_exp_f32_e32 v92, v90
	v_exp_f32_e32 v95, v101
	v_sub_f32_e32 v97, v97, v100
	v_sub_f32_e32 v96, v96, v100
	v_sub_f32_e32 v94, v94, v100
	v_sub_f32_e32 v99, v99, v100
	v_sub_f32_e32 v98, v98, v100
	v_sub_f32_e32 v100, v93, v100
	v_add_f32_e32 v93, v77, v85
	v_add_f32_e32 v104, v86, v87
	v_add_f32_e32 v89, v93, v104
	v_add_f32_e32 v101, 0, v89
	v_add_f32_e32 v104, v88, v91
	v_add_f32_e32 v105, v92, v95
	v_exp_f32_e32 v89, v102
	v_exp_f32_e32 v93, v94
	v_exp_f32_e32 v90, v96
	v_exp_f32_e32 v94, v97
	v_add_f32_e32 v96, v104, v105
	v_add_f32_e32 v101, v96, v101
	v_exp_f32_e32 v96, v100
	v_exp_f32_e32 v97, v103
	v_exp_f32_e32 v98, v98
	v_exp_f32_e32 v99, v99
	v_add_f32_e32 v102, v89, v93
	v_add_f32_e32 v104, v90, v94
	v_add_f32_e32 v100, v102, v104
	v_add_f32_e32 v100, v100, v101
	v_add_f32_e32 v101, v96, v97
	v_add_f32_e32 v102, v98, v99
	v_add_f32_e32 v101, v101, v102
	v_add_f32_e32 v100, v101, v100
	v_mov_b32_e32 v101, v100
	s_nop 1
	v_permlane16_swap_b32_e32 v100, v101
	v_add_f32_e32 v100, v100, v101
	v_mov_b32_e32 v101, v100
	s_nop 1
	v_permlane32_swap_b32_e32 v100, v101
	s_and_saveexec_b64 s[6:7], s[28:29]
	s_cbranch_execz .LBB0_1147
	v_add_f32_e32 v100, v100, v101
	v_rndne_f32_e32 v100, v100
	v_cvt_i32_f32_e32 v100, v100
	v_add_u32_e32 v101, 0x1d000, v224
	ds_add_u32 v101, v100

.LBB0_1151:
	s_or_b64 exec, exec, s[6:7]
	v_cvt_pk_bf16_f32 v50, v39, v40
	v_cvt_pk_bf16_f32 v51, v41, v44
	v_cvt_pk_bf16_f32 v52, v46, v47
	v_cvt_pk_bf16_f32 v53, v48, v49
	v_cvt_pk_bf16_f32 v36, v36, v37
	v_cvt_pk_bf16_f32 v37, v34, v35
	v_mfma_f32_16x16x32_bf16 v[18:21], v[18:21], v[50:53], 0
	v_cvt_pk_bf16_f32 v38, v38, v42
	v_cvt_pk_bf16_f32 v39, v43, v45
	s_movk_i32 s6, 0x110
	v_mul_lo_u32 v171, v83, s6
	v_mfma_f32_16x16x32_bf16 v[2:5], v[2:5], v[36:39], v[18:21]
	v_add3_u32 v76, 0, v171, v226
	s_cmpk_eq_i32 s50, 0xff
	v_mfma_f32_16x16x32_bf16 v[22:25], v[22:25], v[50:53], 0
	v_mfma_f32_16x16x32_bf16 v[6:9], v[6:9], v[36:39], v[22:25]
	s_nop 3
	v_rndne_f32_e32 v2, v2
	v_cvt_i32_f32_e32 v2, v2
	ds_add_u32 v76, v2 offset:49152
	v_rndne_f32_e32 v2, v3
	v_cvt_i32_f32_e32 v2, v2
	v_mfma_f32_16x16x32_bf16 v[26:29], v[26:29], v[50:53], 0
	ds_add_u32 v76, v2 offset:49168
	v_rndne_f32_e32 v2, v4
	v_cvt_i32_f32_e32 v2, v2
	v_mfma_f32_16x16x32_bf16 v[10:13], v[10:13], v[36:39], v[26:29]
	ds_add_u32 v76, v2 offset:49184
	v_rndne_f32_e32 v2, v5
	v_cvt_i32_f32_e32 v2, v2
	v_mfma_f32_16x16x32_bf16 v[30:33], v[30:33], v[50:53], 0
	ds_add_u32 v76, v2 offset:49200
	v_rndne_f32_e32 v2, v6
	v_cvt_i32_f32_e32 v2, v2
	v_mfma_f32_16x16x32_bf16 v[14:17], v[14:17], v[36:39], v[30:33]
	ds_add_u32 v76, v2 offset:49216
	v_rndne_f32_e32 v2, v7
	v_cvt_i32_f32_e32 v2, v2
	ds_add_u32 v76, v2 offset:49232
	v_rndne_f32_e32 v2, v8
	v_cvt_i32_f32_e32 v2, v2
	ds_add_u32 v76, v2 offset:49248
	v_rndne_f32_e32 v2, v9
	v_cvt_i32_f32_e32 v2, v2
	ds_add_u32 v76, v2 offset:49264
	v_rndne_f32_e32 v2, v10
	v_cvt_i32_f32_e32 v2, v2
	ds_add_u32 v76, v2 offset:49280
	v_rndne_f32_e32 v2, v11
	v_cvt_i32_f32_e32 v2, v2
	ds_add_u32 v76, v2 offset:49296
	v_rndne_f32_e32 v2, v12
	v_cvt_i32_f32_e32 v2, v2
	ds_add_u32 v76, v2 offset:49312
	v_rndne_f32_e32 v2, v13
	v_cvt_i32_f32_e32 v2, v2
	ds_add_u32 v76, v2 offset:49328
	v_rndne_f32_e32 v2, v14
	v_cvt_i32_f32_e32 v2, v2
	ds_add_u32 v76, v2 offset:49344
	v_rndne_f32_e32 v2, v15
	v_cvt_i32_f32_e32 v2, v2
	ds_add_u32 v76, v2 offset:49360
	v_rndne_f32_e32 v2, v16
	v_cvt_i32_f32_e32 v2, v2
	ds_add_u32 v76, v2 offset:49376
	v_rndne_f32_e32 v2, v17
	v_cvt_i32_f32_e32 v2, v2
	ds_add_u32 v76, v2 offset:49392
	s_cbranch_scc1 .LBB0_1157
	v_mul_u32_u24_e32 v2, 0x4600, v221
	v_mov_b32_e32 v3, v1
	v_lshl_add_u64 v[2:3], s[38:39], 0, v[2:3]
	s_waitcnt lgkmcnt(0)
	v_lshl_add_u64 v[2:3], v[2:3], 0, v[0:1]
	global_load_dwordx4 v[10:13], v[182:183], off offset:-4096
	v_add_co_u32_e32 v4, vcc, 0x11000, v2
	v_lshl_add_u64 v[102:103], v[66:67], 0, v[0:1]
	s_nop 0
	v_addc_co_u32_e32 v5, vcc, 0, v3, vcc
	global_load_dwordx4 v[22:25], v[182:183], off offset:-2048
	v_add_co_u32_e32 v6, vcc, 0x8c000, v2
	v_lshl_add_u64 v[98:99], v[70:71], 0, v[0:1]
	s_nop 0
	v_addc_co_u32_e32 v7, vcc, 0, v3, vcc
	global_load_dwordx4 v[26:29], v[182:183], off
	global_load_dwordx4 v[30:33], v[182:183], off offset:-3072
	v_add_co_u32_e32 v2, vcc, 0x9d000, v2
	v_lshl_add_u64 v[106:107], v[72:73], 0, v[0:1]
	s_nop 0
	v_addc_co_u32_e32 v3, vcc, 0, v3, vcc
	global_load_dwordx4 v[38:41], v[182:183], off offset:2048
	global_load_dwordx4 v[50:53], v[182:183], off offset:-1024
	global_load_dwordx4 v[46:49], v[182:183], off offset:1024
	global_load_dwordx4 v[34:37], v[182:183], off offset:3072
	v_add_u32_e32 v2, 0x1d400, v224
	ds_read_b32 v2, v2
	ds_read_b128 v[18:21], v81
	ds_read_b128 v[82:85], v82
	v_add_co_u32_e32 v8, vcc, 0x80000, v102
	v_lshl_add_u64 v[6:7], v[68:69], 0, v[0:1]
	s_waitcnt lgkmcnt(2)
	v_sub_f32_e32 v54, 0x41200000, v2
	v_mov_b32_e32 v55, v54
	v_mov_b32_e32 v56, v54
	v_mov_b32_e32 v57, v54
	v_addc_co_u32_e32 v9, vcc, 0, v103, vcc
	v_add_co_u32_e32 v100, vcc, 0x100000, v102
	global_load_dwordx4 v[14:17], v[184:185], off offset:-4096
	global_load_dwordx4 v[2:5], v[184:185], off offset:-3072
	v_addc_co_u32_e32 v101, vcc, 0, v103, vcc
	global_load_dwordx4 v[42:45], v[184:185], off offset:-2048
	s_nop 0
	global_load_dwordx4 v[6:9], v[184:185], off offset:-1024
	s_waitcnt vmcnt(9) lgkmcnt(1)
	v_mfma_f32_16x16x32_bf16 v[86:89], v[26:29], v[18:21], v[54:57]
	v_mfma_f32_16x16x32_bf16 v[58:61], v[10:13], v[18:21], v[54:57]
	v_mfma_f32_16x16x32_bf16 v[62:65], v[22:25], v[18:21], v[54:57]
	s_waitcnt vmcnt(8) lgkmcnt(0)
	v_mfma_f32_16x16x32_bf16 v[90:93], v[30:33], v[82:85], v[58:61]
	s_nop 4
	v_add_co_u32_e32 v58, vcc, 0x180000, v102
	s_waitcnt vmcnt(7)
	v_mfma_f32_16x16x32_bf16 v[94:97], v[38:41], v[18:21], v[54:57]
	v_addc_co_u32_e32 v59, vcc, 0, v103, vcc
	s_nop 1
	global_load_dwordx4 v[54:57], v[184:185], off
	global_load_dwordx4 v[18:21], v[184:185], off offset:1024
	s_waitcnt vmcnt(8)
	v_mfma_f32_16x16x32_bf16 v[98:101], v[50:53], v[82:85], v[62:65]
	s_nop 2
	global_load_dwordx4 v[62:65], v[184:185], off offset:2048
	s_nop 0
	global_load_dwordx4 v[58:61], v[184:185], off offset:3072
	v_exp_f32_e32 v78, v90
	v_exp_f32_e32 v81, v91
	s_waitcnt vmcnt(9)
	v_mfma_f32_16x16x32_bf16 v[102:105], v[46:49], v[82:85], v[86:89]
	v_exp_f32_e32 v90, v100
	v_exp_f32_e32 v91, v101
	s_waitcnt vmcnt(8)
	v_mfma_f32_16x16x32_bf16 v[94:97], v[34:37], v[82:85], v[94:97]
	v_exp_f32_e32 v82, v92
	v_exp_f32_e32 v83, v93
	v_exp_f32_e32 v88, v98
	v_exp_f32_e32 v89, v99
	v_exp_f32_e32 v84, v102
	v_exp_f32_e32 v86, v103
	v_exp_f32_e32 v85, v104
	v_exp_f32_e32 v87, v105
	v_exp_f32_e32 v92, v94
	v_exp_f32_e32 v93, v95
	v_exp_f32_e32 v94, v96
	v_exp_f32_e32 v95, v97
	v_add_f32_e32 v98, v78, v81
	v_add_f32_e32 v99, v82, v83
	v_add_f32_e32 v96, v98, v99
	v_add_f32_e32 v97, v88, v89
	v_add_f32_e32 v98, v90, v91
	v_add_f32_e32 v96, 0, v96
	v_add_f32_e32 v97, v97, v98
	v_add_f32_e32 v98, v84, v86
	v_add_f32_e32 v99, v85, v87
	v_add_f32_e32 v96, v96, v97
	v_add_f32_e32 v97, v98, v99
	v_add_f32_e32 v98, v92, v93
	v_add_f32_e32 v99, v94, v95
	v_add_f32_e32 v96, v96, v97
	v_add_f32_e32 v97, v98, v99
	v_add_f32_e32 v96, v96, v97
	v_mov_b32_e32 v97, v96
	s_nop 1
	v_permlane16_swap_b32_e32 v96, v97
	v_add_f32_e32 v96, v96, v97
	v_mov_b32_e32 v97, v96
	s_nop 1
	v_permlane32_swap_b32_e32 v96, v97
	s_and_saveexec_b64 s[6:7], s[28:29]
	s_cbranch_execz .LBB0_1154
	v_add_f32_e32 v96, v96, v97
	v_rndne_f32_e32 v96, v96
	v_cvt_i32_f32_e32 v96, v96
	v_add_u32_e32 v97, 0x1d000, v224
	ds_add_u32 v97, v96
